# gate/up tail weight conversion: non-temporal hint on the converted bf16 weight stores too
# baseline (speedup 1.0000x reference)
.LBB0_863:
	s_waitcnt vmcnt(0)
	v_pk_mul_f32 v[2:3], v[2:3], v[0:1] op_sel_hi:[1,0]
	v_add_u32_e32 v6, 0x2cb0, v98
	ds_write2_b32 v6, v2, v3 offset1:1
	v_pk_mul_f32 v[2:3], v[4:5], v[0:1] op_sel_hi:[1,0]
	v_add_u32_e32 v0, 0x2cb8, v98
	ds_write2_b32 v0, v2, v3 offset1:1
	s_waitcnt lgkmcnt(0)
	v_add_u32_e32 v0, 0x400, v87
	ds_read2_b32 v[8:9], v87 offset0:65 offset1:73
	ds_read2_b32 v[10:11], v87 offset1:8
	ds_read2_b32 v[12:13], v87 offset0:130 offset1:138
	ds_read2_b32 v[14:15], v87 offset0:195 offset1:203
	ds_read2_b32 v[16:17], v0 offset0:4 offset1:12
	ds_read2_b32 v[18:19], v0 offset0:69 offset1:77
	ds_read2_b32 v[20:21], v0 offset0:134 offset1:142
	ds_read2_b32 v[22:23], v0 offset0:199 offset1:207
	v_add_u32_e32 v24, s10, v86
	v_ashrrev_i32_e32 v25, 31, v24
	v_lshl_add_u64 v[2:3], s[12:13], 1, v[76:77]
	v_lshlrev_b64 v[26:27], 11, v[24:25]
	s_waitcnt lgkmcnt(6)
	v_cvt_pk_bf16_f32 v4, v10, v8
	s_waitcnt lgkmcnt(4)
	v_cvt_pk_bf16_f32 v5, v12, v14
	s_waitcnt lgkmcnt(2)
	v_cvt_pk_bf16_f32 v6, v16, v18
	s_waitcnt lgkmcnt(0)
	v_cvt_pk_bf16_f32 v7, v20, v22
	v_lshl_add_u64 v[26:27], v[2:3], 0, v[26:27]
	v_add_u32_e32 v8, 8, v24
	global_store_dwordx4 v[26:27], v[4:7], off nt
	v_add_u32_e32 v26, 16, v24
	v_ashrrev_i32_e32 v27, 31, v26
	v_cvt_pk_bf16_f32 v4, v11, v9
	v_ashrrev_i32_e32 v9, 31, v8
	v_lshlrev_b64 v[8:9], 11, v[8:9]
	v_cvt_pk_bf16_f32 v5, v13, v15
	v_cvt_pk_bf16_f32 v6, v17, v19
	v_cvt_pk_bf16_f32 v7, v21, v23
	v_lshl_add_u64 v[8:9], v[2:3], 0, v[8:9]
	global_store_dwordx4 v[8:9], v[4:7], off nt
	ds_read2_b32 v[8:9], v87 offset0:81 offset1:89
	ds_read2_b32 v[10:11], v87 offset0:16 offset1:24
	ds_read2_b32 v[12:13], v87 offset0:146 offset1:154
	ds_read2_b32 v[14:15], v87 offset0:211 offset1:219
	ds_read2_b32 v[16:17], v0 offset0:20 offset1:28
	ds_read2_b32 v[18:19], v0 offset0:85 offset1:93
	ds_read2_b32 v[20:21], v0 offset0:150 offset1:158
	ds_read2_b32 v[22:23], v0 offset0:215 offset1:223
	v_lshlrev_b64 v[26:27], 11, v[26:27]
	s_waitcnt lgkmcnt(6)
	v_cvt_pk_bf16_f32 v4, v10, v8
	s_waitcnt lgkmcnt(4)
	v_cvt_pk_bf16_f32 v5, v12, v14
	s_waitcnt lgkmcnt(2)
	v_cvt_pk_bf16_f32 v6, v16, v18
	s_waitcnt lgkmcnt(0)
	v_cvt_pk_bf16_f32 v7, v20, v22
	v_lshl_add_u64 v[26:27], v[2:3], 0, v[26:27]
	v_add_u32_e32 v8, 24, v24
	global_store_dwordx4 v[26:27], v[4:7], off nt
	v_add_u32_e32 v26, 32, v24
	v_ashrrev_i32_e32 v27, 31, v26
	v_cvt_pk_bf16_f32 v4, v11, v9
	v_ashrrev_i32_e32 v9, 31, v8
	v_lshlrev_b64 v[8:9], 11, v[8:9]
	v_cvt_pk_bf16_f32 v5, v13, v15
	v_cvt_pk_bf16_f32 v6, v17, v19
	v_cvt_pk_bf16_f32 v7, v21, v23
	v_lshl_add_u64 v[8:9], v[2:3], 0, v[8:9]
	global_store_dwordx4 v[8:9], v[4:7], off nt
	ds_read2_b32 v[8:9], v87 offset0:32 offset1:40
	ds_read2_b32 v[10:11], v87 offset0:97 offset1:105
	ds_read2_b32 v[12:13], v87 offset0:162 offset1:170
	ds_read2_b32 v[14:15], v87 offset0:227 offset1:235
	ds_read2_b32 v[16:17], v0 offset0:36 offset1:44
	ds_read2_b32 v[18:19], v0 offset0:101 offset1:109
	ds_read2_b32 v[20:21], v0 offset0:166 offset1:174
	ds_read2_b32 v[22:23], v0 offset0:231 offset1:239
	v_lshlrev_b64 v[26:27], 11, v[26:27]
	s_waitcnt lgkmcnt(6)
	v_cvt_pk_bf16_f32 v4, v8, v10
	s_waitcnt lgkmcnt(4)
	v_cvt_pk_bf16_f32 v5, v12, v14
	s_waitcnt lgkmcnt(2)
	v_cvt_pk_bf16_f32 v6, v16, v18
	s_waitcnt lgkmcnt(0)
	v_cvt_pk_bf16_f32 v7, v20, v22
	v_lshl_add_u64 v[26:27], v[2:3], 0, v[26:27]
	v_add_u32_e32 v8, 40, v24
	global_store_dwordx4 v[26:27], v[4:7], off nt
	v_add_u32_e32 v26, 48, v24
	v_ashrrev_i32_e32 v27, 31, v26
	v_cvt_pk_bf16_f32 v4, v9, v11
	v_ashrrev_i32_e32 v9, 31, v8
	v_lshlrev_b64 v[8:9], 11, v[8:9]
	v_cvt_pk_bf16_f32 v5, v13, v15
	v_cvt_pk_bf16_f32 v6, v17, v19
	v_cvt_pk_bf16_f32 v7, v21, v23
	v_lshl_add_u64 v[8:9], v[2:3], 0, v[8:9]
	global_store_dwordx4 v[8:9], v[4:7], off nt
	ds_read2_b32 v[8:9], v87 offset0:48 offset1:56
	ds_read2_b32 v[10:11], v87 offset0:113 offset1:121
	ds_read2_b32 v[12:13], v87 offset0:178 offset1:186
	ds_read2_b32 v[14:15], v87 offset0:243 offset1:251
	ds_read2_b32 v[16:17], v0 offset0:52 offset1:60
	ds_read2_b32 v[18:19], v0 offset0:117 offset1:125
	ds_read2_b32 v[20:21], v0 offset0:182 offset1:190
	ds_read2_b32 v[22:23], v0 offset0:247 offset1:255
	v_lshlrev_b64 v[26:27], 11, v[26:27]
	s_waitcnt lgkmcnt(6)
	v_cvt_pk_bf16_f32 v4, v8, v10
	s_waitcnt lgkmcnt(4)
	v_cvt_pk_bf16_f32 v5, v12, v14
	s_waitcnt lgkmcnt(2)
	v_cvt_pk_bf16_f32 v6, v16, v18
	s_waitcnt lgkmcnt(0)
	v_cvt_pk_bf16_f32 v7, v20, v22
	v_lshl_add_u64 v[26:27], v[2:3], 0, v[26:27]
	v_add_u32_e32 v8, 56, v24
	global_store_dwordx4 v[26:27], v[4:7], off nt
	s_nop 1
	v_cvt_pk_bf16_f32 v4, v9, v11
	v_ashrrev_i32_e32 v9, 31, v8
	v_lshlrev_b64 v[8:9], 11, v[8:9]
	v_cvt_pk_bf16_f32 v5, v13, v15
	v_cvt_pk_bf16_f32 v6, v17, v19
	v_cvt_pk_bf16_f32 v7, v21, v23
	v_lshl_add_u64 v[2:3], v[2:3], 0, v[8:9]
	global_store_dwordx4 v[2:3], v[4:7], off nt
	s_waitcnt lgkmcnt(0)

.LBB0_865:
	s_cmpk_gt_i32 s18, 0x2ff
	s_mov_b64 s[10:11], -1
	s_cbranch_scc0 .LBB0_875
	s_cmpk_gt_u32 s18, 0x3ff
	s_cbranch_scc0 .LBB0_872
	s_cmpk_gt_u32 s18, 0x43f
	v_lshlrev_b32_e32 v0, 2, v68
	s_cbranch_scc0 .LBB0_869
	s_add_i32 s0, s18, 0xfffffbc0
	s_lshr_b32 s0, s0, 6
	v_readlane_b32 s36, v253, 1
	s_lshl_b64 s[10:11], s[0:1], 20
	v_readlane_b32 s42, v253, 7
	v_readlane_b32 s43, v253, 8
	s_add_u32 s12, s42, s10
	s_addc_u32 s13, s43, s11
	s_and_b32 s14, s7, 64
	s_lshl_b32 s0, s0, 7
	s_and_b32 s11, s9, 0x7c0
	s_or_b32 s10, s0, s14
	s_lshl_b32 s0, s14, 2
	s_add_u32 s12, s12, s0
	v_or_b32_e32 v4, s11, v66
	s_addc_u32 s13, s13, 0
	v_lshl_add_u64 v[2:3], s[12:13], 0, v[0:1]
	v_lshlrev_b32_e32 v4, 9, v4
	v_mov_b32_e32 v5, v1
	v_lshl_add_u64 v[58:59], v[2:3], 0, v[4:5]
	global_load_dwordx4 v[2:5], v[58:59], off nt
	global_load_dwordx4 v[6:9], v[58:59], off offset:2048 nt
	s_movk_i32 s0, 0x1000
	v_add_co_u32_e32 v14, vcc, s0, v58
	s_movk_i32 s0, 0x2000
	s_nop 0
	v_addc_co_u32_e32 v15, vcc, 0, v59, vcc
	v_add_co_u32_e32 v22, vcc, s0, v58
	s_movk_i32 s0, 0x3000
	s_nop 0
	v_addc_co_u32_e32 v23, vcc, 0, v59, vcc
	global_load_dwordx4 v[10:13], v[22:23], off offset:-4096
	s_nop 0
	global_load_dwordx4 v[14:17], v[14:15], off offset:2048 nt
	s_nop 0
	global_load_dwordx4 v[18:21], v[22:23], off nt
	s_nop 0
	global_load_dwordx4 v[22:25], v[22:23], off offset:2048 nt
	v_add_co_u32_e32 v30, vcc, s0, v58
	s_movk_i32 s0, 0x4000
	s_nop 0
	v_addc_co_u32_e32 v31, vcc, 0, v59, vcc
	v_add_co_u32_e32 v38, vcc, s0, v58
	s_movk_i32 s0, 0x5000
	s_nop 0
	v_addc_co_u32_e32 v39, vcc, 0, v59, vcc
	global_load_dwordx4 v[26:29], v[38:39], off offset:-4096
	s_nop 0
	global_load_dwordx4 v[30:33], v[30:31], off offset:2048 nt
	s_nop 0
	global_load_dwordx4 v[34:37], v[38:39], off nt
	s_nop 0
	global_load_dwordx4 v[38:41], v[38:39], off offset:2048 nt
	v_add_co_u32_e32 v46, vcc, s0, v58
	s_movk_i32 s0, 0x6000
	s_nop 0
	v_addc_co_u32_e32 v47, vcc, 0, v59, vcc
	v_add_co_u32_e32 v54, vcc, s0, v58
	s_movk_i32 s0, 0x7000
	s_nop 0
	v_addc_co_u32_e32 v55, vcc, 0, v59, vcc
	global_load_dwordx4 v[42:45], v[54:55], off offset:-4096
	s_nop 0
	global_load_dwordx4 v[46:49], v[46:47], off offset:2048 nt
	s_nop 0
	global_load_dwordx4 v[50:53], v[54:55], off nt
	s_nop 0
	global_load_dwordx4 v[54:57], v[54:55], off offset:2048 nt
	v_add_co_u32_e32 v62, vcc, s0, v58
	s_lshl_b32 s0, s11, 1
	s_nop 0
	v_addc_co_u32_e32 v63, vcc, 0, v59, vcc
	global_load_dwordx4 v[58:61], v[62:63], off nt
	s_nop 0
	global_load_dwordx4 v[62:65], v[62:63], off offset:2048 nt
	v_readlane_b32 s37, v253, 2
	v_readlane_b32 s38, v253, 3
	v_readlane_b32 s39, v253, 4
	v_readlane_b32 s40, v253, 5
	v_readlane_b32 s41, v253, 6
	v_readlane_b32 s44, v253, 9
	v_readlane_b32 s45, v253, 10
	v_readlane_b32 s46, v253, 11
	v_readlane_b32 s47, v253, 12
	v_readlane_b32 s48, v253, 13
	v_readlane_b32 s49, v253, 14
	v_readlane_b32 s50, v253, 15
	v_readlane_b32 s51, v253, 16
	s_waitcnt vmcnt(0)
	ds_write2_b32 v69, v2, v3 offset1:1
	ds_write2_b32 v69, v4, v5 offset0:2 offset1:3
	v_add_u32_e32 v2, 0x410, v69
	ds_write2_b32 v2, v6, v7 offset1:1
	v_add_u32_e32 v2, 0x418, v69
	ds_write2_b32 v2, v8, v9 offset1:1
	v_add_u32_e32 v2, 0x820, v69
	ds_write2_b32 v2, v10, v11 offset1:1
	v_add_u32_e32 v2, 0x828, v69
	ds_write2_b32 v2, v12, v13 offset1:1
	v_add_u32_e32 v2, 0xc30, v69
	ds_write2_b32 v2, v14, v15 offset1:1
	v_add_u32_e32 v2, 0xc38, v69
	ds_write2_b32 v2, v16, v17 offset1:1
	v_add_u32_e32 v2, 0x1040, v69
	ds_write2_b32 v2, v18, v19 offset1:1
	v_add_u32_e32 v2, 0x1048, v69
	ds_write2_b32 v2, v20, v21 offset1:1
	v_add_u32_e32 v2, 0x1450, v69
	ds_write2_b32 v2, v22, v23 offset1:1
	v_add_u32_e32 v2, 0x1458, v69
	ds_write2_b32 v2, v24, v25 offset1:1
	v_add_u32_e32 v2, 0x1860, v69
	ds_write2_b32 v2, v26, v27 offset1:1
	v_add_u32_e32 v2, 0x1868, v69
	ds_write2_b32 v2, v28, v29 offset1:1
	v_add_u32_e32 v2, 0x1c70, v69
	ds_write2_b32 v2, v30, v31 offset1:1
	v_add_u32_e32 v2, 0x1c78, v69
	ds_write2_b32 v2, v32, v33 offset1:1
	v_add_u32_e32 v2, 0x2080, v69
	ds_write2_b32 v2, v34, v35 offset1:1
	v_add_u32_e32 v2, 0x2088, v69
	ds_write2_b32 v2, v36, v37 offset1:1
	v_add_u32_e32 v2, 0x2490, v69
	ds_write2_b32 v2, v38, v39 offset1:1
	v_add_u32_e32 v2, 0x2498, v69
	ds_write2_b32 v2, v40, v41 offset1:1
	v_add_u32_e32 v2, 0x28a0, v69
	ds_write2_b32 v2, v42, v43 offset1:1
	v_add_u32_e32 v2, 0x28a8, v69
	ds_write2_b32 v2, v44, v45 offset1:1
	v_add_u32_e32 v2, 0x2cb0, v69
	ds_write2_b32 v2, v46, v47 offset1:1
	v_add_u32_e32 v2, 0x2cb8, v69
	ds_write2_b32 v2, v48, v49 offset1:1
	v_add_u32_e32 v2, 0x30c0, v69
	ds_write2_b32 v2, v50, v51 offset1:1
	v_add_u32_e32 v2, 0x30c8, v69
	ds_write2_b32 v2, v52, v53 offset1:1
	v_add_u32_e32 v2, 0x34d0, v69
	ds_write2_b32 v2, v54, v55 offset1:1
	v_add_u32_e32 v2, 0x34d8, v69
	ds_write2_b32 v2, v56, v57 offset1:1
	v_add_u32_e32 v2, 0x38e0, v69
	ds_write2_b32 v2, v58, v59 offset1:1
	v_add_u32_e32 v2, 0x38e8, v69
	ds_write2_b32 v2, v60, v61 offset1:1
	v_add_u32_e32 v2, 0x3cf0, v69
	ds_write2_b32 v2, v62, v63 offset1:1
	v_add_u32_e32 v2, 0x3cf8, v69
	ds_write2_b32 v2, v64, v65 offset1:1
	s_waitcnt lgkmcnt(0)
	v_add_u32_e32 v26, 0x400, v87
	ds_read2_b32 v[8:9], v87 offset0:65 offset1:73
	ds_read2_b32 v[10:11], v87 offset1:8
	ds_read2_b32 v[12:13], v87 offset0:130 offset1:138
	ds_read2_b32 v[14:15], v87 offset0:195 offset1:203
	ds_read2_b32 v[16:17], v26 offset0:4 offset1:12
	ds_read2_b32 v[18:19], v26 offset0:69 offset1:77
	ds_read2_b32 v[20:21], v26 offset0:134 offset1:142
	ds_read2_b32 v[22:23], v26 offset0:199 offset1:207
	v_or_b32_e32 v24, s10, v86
	v_mov_b32_e32 v25, v1
	v_lshl_add_u64 v[2:3], v[70:71], 0, s[0:1]
	v_lshlrev_b64 v[24:25], 12, v[24:25]
	s_waitcnt lgkmcnt(6)
	v_cvt_pk_bf16_f32 v4, v10, v8
	s_waitcnt lgkmcnt(4)
	v_cvt_pk_bf16_f32 v5, v12, v14
	s_waitcnt lgkmcnt(2)
	v_cvt_pk_bf16_f32 v6, v16, v18
	s_waitcnt lgkmcnt(0)
	v_cvt_pk_bf16_f32 v7, v20, v22
	v_lshl_add_u64 v[24:25], v[2:3], 0, v[24:25]
	global_store_dwordx4 v[24:25], v[4:7], off nt
	v_or_b32_e32 v8, s10, v88
	v_or_b32_e32 v24, s10, v89
	v_cvt_pk_bf16_f32 v4, v11, v9
	v_mov_b32_e32 v9, v1
	v_lshlrev_b64 v[8:9], 12, v[8:9]
	v_cvt_pk_bf16_f32 v5, v13, v15
	v_cvt_pk_bf16_f32 v6, v17, v19
	v_cvt_pk_bf16_f32 v7, v21, v23
	v_lshl_add_u64 v[8:9], v[2:3], 0, v[8:9]
	global_store_dwordx4 v[8:9], v[4:7], off nt
	ds_read2_b32 v[8:9], v87 offset0:81 offset1:89
	ds_read2_b32 v[10:11], v87 offset0:16 offset1:24
	ds_read2_b32 v[12:13], v87 offset0:146 offset1:154
	ds_read2_b32 v[14:15], v87 offset0:211 offset1:219
	ds_read2_b32 v[16:17], v26 offset0:20 offset1:28
	ds_read2_b32 v[18:19], v26 offset0:85 offset1:93
	ds_read2_b32 v[20:21], v26 offset0:150 offset1:158
	ds_read2_b32 v[22:23], v26 offset0:215 offset1:223
	v_mov_b32_e32 v25, v1
	v_lshlrev_b64 v[24:25], 12, v[24:25]
	s_waitcnt lgkmcnt(6)
	v_cvt_pk_bf16_f32 v4, v10, v8
	s_waitcnt lgkmcnt(4)
	v_cvt_pk_bf16_f32 v5, v12, v14
	s_waitcnt lgkmcnt(2)
	v_cvt_pk_bf16_f32 v6, v16, v18
	s_waitcnt lgkmcnt(0)
	v_cvt_pk_bf16_f32 v7, v20, v22
	v_lshl_add_u64 v[24:25], v[2:3], 0, v[24:25]
	global_store_dwordx4 v[24:25], v[4:7], off nt
	v_or_b32_e32 v8, s10, v90
	v_or_b32_e32 v24, s10, v91
	v_cvt_pk_bf16_f32 v4, v11, v9
	v_mov_b32_e32 v9, v1
	v_lshlrev_b64 v[8:9], 12, v[8:9]
	v_cvt_pk_bf16_f32 v5, v13, v15
	v_cvt_pk_bf16_f32 v6, v17, v19
	v_cvt_pk_bf16_f32 v7, v21, v23
	v_lshl_add_u64 v[8:9], v[2:3], 0, v[8:9]
	global_store_dwordx4 v[8:9], v[4:7], off nt
	ds_read2_b32 v[8:9], v87 offset0:32 offset1:40
	ds_read2_b32 v[10:11], v87 offset0:97 offset1:105
	ds_read2_b32 v[12:13], v87 offset0:162 offset1:170
	ds_read2_b32 v[14:15], v87 offset0:227 offset1:235
	ds_read2_b32 v[16:17], v26 offset0:36 offset1:44
	ds_read2_b32 v[18:19], v26 offset0:101 offset1:109
	ds_read2_b32 v[20:21], v26 offset0:166 offset1:174
	ds_read2_b32 v[22:23], v26 offset0:231 offset1:239
	v_mov_b32_e32 v25, v1
	v_lshlrev_b64 v[24:25], 12, v[24:25]
	s_waitcnt lgkmcnt(6)
	v_cvt_pk_bf16_f32 v4, v8, v10
	s_waitcnt lgkmcnt(4)
	v_cvt_pk_bf16_f32 v5, v12, v14
	s_waitcnt lgkmcnt(2)
	v_cvt_pk_bf16_f32 v6, v16, v18
	s_waitcnt lgkmcnt(0)
	v_cvt_pk_bf16_f32 v7, v20, v22
	v_lshl_add_u64 v[24:25], v[2:3], 0, v[24:25]
	global_store_dwordx4 v[24:25], v[4:7], off nt
	v_or_b32_e32 v8, s10, v92
	v_or_b32_e32 v24, s10, v93
	v_cvt_pk_bf16_f32 v4, v9, v11
	v_mov_b32_e32 v9, v1
	v_lshlrev_b64 v[8:9], 12, v[8:9]
	v_cvt_pk_bf16_f32 v5, v13, v15
	v_cvt_pk_bf16_f32 v6, v17, v19
	v_cvt_pk_bf16_f32 v7, v21, v23
	v_lshl_add_u64 v[8:9], v[2:3], 0, v[8:9]
	global_store_dwordx4 v[8:9], v[4:7], off nt
	ds_read2_b32 v[8:9], v87 offset0:48 offset1:56
	ds_read2_b32 v[10:11], v87 offset0:113 offset1:121
	ds_read2_b32 v[12:13], v87 offset0:178 offset1:186
	ds_read2_b32 v[14:15], v87 offset0:243 offset1:251
	ds_read2_b32 v[16:17], v26 offset0:52 offset1:60
	ds_read2_b32 v[18:19], v26 offset0:117 offset1:125
	ds_read2_b32 v[20:21], v26 offset0:182 offset1:190
	ds_read2_b32 v[22:23], v26 offset0:247 offset1:255
	v_mov_b32_e32 v25, v1
	v_lshlrev_b64 v[24:25], 12, v[24:25]
	s_waitcnt lgkmcnt(6)
	v_cvt_pk_bf16_f32 v4, v8, v10
	s_waitcnt lgkmcnt(4)
	v_cvt_pk_bf16_f32 v5, v12, v14
	s_waitcnt lgkmcnt(2)
	v_cvt_pk_bf16_f32 v6, v16, v18
	s_waitcnt lgkmcnt(0)
	v_cvt_pk_bf16_f32 v7, v20, v22
	v_lshl_add_u64 v[24:25], v[2:3], 0, v[24:25]
	global_store_dwordx4 v[24:25], v[4:7], off nt
	v_or_b32_e32 v8, s10, v94
	s_mov_b64 s[10:11], 0
	v_cvt_pk_bf16_f32 v4, v9, v11
	v_mov_b32_e32 v9, v1
	v_lshlrev_b64 v[8:9], 12, v[8:9]
	v_cvt_pk_bf16_f32 v5, v13, v15
	v_cvt_pk_bf16_f32 v6, v17, v19
	v_cvt_pk_bf16_f32 v7, v21, v23
	v_lshl_add_u64 v[2:3], v[2:3], 0, v[8:9]
	global_store_dwordx4 v[2:3], v[4:7], off nt
	s_waitcnt lgkmcnt(0)
.LBB0_869:
	s_andn2_b64 vcc, exec, s[10:11]
	s_cbranch_vccnz .LBB0_871
	s_add_i32 s0, s18, 0xfffffc00
	s_lshr_b32 s0, s0, 4
	v_readlane_b32 s36, v253, 1
	s_lshl_b64 s[10:11], s[0:1], 18
	v_readlane_b32 s50, v253, 15
	v_readlane_b32 s51, v253, 16
	s_add_u32 s12, s50, s10
	s_addc_u32 s13, s51, s11
	s_and_b32 s14, s7, 0xc0
	s_lshl_b32 s0, s0, 8
	s_and_b32 s11, s16, 0xc0
	s_or_b32 s10, s0, s14
	s_lshl_b32 s0, s14, 2
	s_add_u32 s12, s12, s0
	v_or_b32_e32 v4, s11, v66
	s_addc_u32 s13, s13, 0
	v_lshl_add_u64 v[2:3], s[12:13], 0, v[0:1]
	v_lshlrev_b32_e32 v0, 10, v4
	v_lshl_add_u64 v[62:63], v[2:3], 0, v[0:1]
	s_movk_i32 s0, 0x2000
	v_add_co_u32_e32 v10, vcc, s0, v62
	global_load_dwordx4 v[2:5], v[62:63], off nt
	s_nop 0
	v_addc_co_u32_e32 v11, vcc, 0, v63, vcc
	global_load_dwordx4 v[6:9], v[10:11], off offset:-4096
	s_nop 0
	global_load_dwordx4 v[10:13], v[10:11], off nt
	s_movk_i32 s0, 0x4000
	v_add_co_u32_e32 v18, vcc, s0, v62
	s_movk_i32 s0, 0x6000
	s_nop 0
	v_addc_co_u32_e32 v19, vcc, 0, v63, vcc
	global_load_dwordx4 v[14:17], v[18:19], off offset:-4096
	s_nop 0
	global_load_dwordx4 v[18:21], v[18:19], off nt
	v_add_co_u32_e32 v26, vcc, s0, v62
	s_mov_b32 s0, 0x8000
	s_nop 0
	v_addc_co_u32_e32 v27, vcc, 0, v63, vcc
	global_load_dwordx4 v[22:25], v[26:27], off offset:-4096
	s_nop 0
	global_load_dwordx4 v[26:29], v[26:27], off nt
	v_add_co_u32_e32 v34, vcc, s0, v62
	s_mov_b32 s0, 0xa000
	s_nop 0
	v_addc_co_u32_e32 v35, vcc, 0, v63, vcc
	global_load_dwordx4 v[30:33], v[34:35], off offset:-4096
	s_nop 0
	global_load_dwordx4 v[34:37], v[34:35], off nt
	v_add_co_u32_e32 v42, vcc, s0, v62
	s_mov_b32 s0, 0xc000
	s_nop 0
	v_addc_co_u32_e32 v43, vcc, 0, v63, vcc
	global_load_dwordx4 v[38:41], v[42:43], off offset:-4096
	s_nop 0
	global_load_dwordx4 v[42:45], v[42:43], off nt
	v_add_co_u32_e32 v50, vcc, s0, v62
	s_mov_b32 s0, 0xe000
	s_nop 0
	v_addc_co_u32_e32 v51, vcc, 0, v63, vcc
	global_load_dwordx4 v[46:49], v[50:51], off offset:-4096
	s_nop 0
	global_load_dwordx4 v[50:53], v[50:51], off nt
	v_add_co_u32_e32 v58, vcc, s0, v62
	s_mov_b32 s0, 0xf000
	s_nop 0
	v_addc_co_u32_e32 v59, vcc, 0, v63, vcc
	global_load_dwordx4 v[54:57], v[58:59], off offset:-4096
	s_nop 0
	global_load_dwordx4 v[58:61], v[58:59], off nt
	v_add_co_u32_e32 v62, vcc, s0, v62
	v_add_u32_e32 v0, 0x410, v69
	s_nop 0
	v_addc_co_u32_e32 v63, vcc, 0, v63, vcc
	global_load_dwordx4 v[62:65], v[62:63], off nt
	s_lshl_b32 s0, s11, 1
	v_readlane_b32 s37, v253, 2
	v_readlane_b32 s38, v253, 3
	v_readlane_b32 s39, v253, 4
	v_readlane_b32 s40, v253, 5
	v_readlane_b32 s41, v253, 6
	v_readlane_b32 s42, v253, 7
	v_readlane_b32 s43, v253, 8
	v_readlane_b32 s44, v253, 9
	v_readlane_b32 s45, v253, 10
	v_readlane_b32 s46, v253, 11
	v_readlane_b32 s47, v253, 12
	v_readlane_b32 s48, v253, 13
	v_readlane_b32 s49, v253, 14
	s_waitcnt vmcnt(0)
	ds_write2_b32 v69, v2, v3 offset1:1
	ds_write2_b32 v69, v4, v5 offset0:2 offset1:3
	v_lshl_add_u64 v[2:3], v[72:73], 0, s[0:1]
	ds_write2_b32 v0, v6, v7 offset1:1
	v_add_u32_e32 v0, 0x418, v69
	ds_write2_b32 v0, v8, v9 offset1:1
	v_add_u32_e32 v0, 0x820, v69
	ds_write2_b32 v0, v10, v11 offset1:1
	v_add_u32_e32 v0, 0x828, v69
	ds_write2_b32 v0, v12, v13 offset1:1
	v_add_u32_e32 v0, 0xc30, v69
	ds_write2_b32 v0, v14, v15 offset1:1
	v_add_u32_e32 v0, 0xc38, v69
	ds_write2_b32 v0, v16, v17 offset1:1
	v_add_u32_e32 v0, 0x1040, v69
	ds_write2_b32 v0, v18, v19 offset1:1
	v_add_u32_e32 v0, 0x1048, v69
	ds_write2_b32 v0, v20, v21 offset1:1
	v_add_u32_e32 v0, 0x1450, v69
	ds_write2_b32 v0, v22, v23 offset1:1
	v_add_u32_e32 v0, 0x1458, v69
	ds_write2_b32 v0, v24, v25 offset1:1
	v_add_u32_e32 v0, 0x1860, v69
	ds_write2_b32 v0, v26, v27 offset1:1
	v_add_u32_e32 v0, 0x1868, v69
	ds_write2_b32 v0, v28, v29 offset1:1
	v_add_u32_e32 v0, 0x1c70, v69
	ds_write2_b32 v0, v30, v31 offset1:1
	v_add_u32_e32 v0, 0x1c78, v69
	ds_write2_b32 v0, v32, v33 offset1:1
	v_add_u32_e32 v0, 0x2080, v69
	ds_write2_b32 v0, v34, v35 offset1:1
	v_add_u32_e32 v0, 0x2088, v69
	ds_write2_b32 v0, v36, v37 offset1:1
	v_add_u32_e32 v0, 0x2490, v69
	ds_write2_b32 v0, v38, v39 offset1:1
	v_add_u32_e32 v0, 0x2498, v69
	ds_write2_b32 v0, v40, v41 offset1:1
	v_add_u32_e32 v0, 0x28a0, v69
	ds_write2_b32 v0, v42, v43 offset1:1
	v_add_u32_e32 v0, 0x28a8, v69
	ds_write2_b32 v0, v44, v45 offset1:1
	v_add_u32_e32 v0, 0x2cb0, v69
	ds_write2_b32 v0, v46, v47 offset1:1
	v_add_u32_e32 v0, 0x2cb8, v69
	ds_write2_b32 v0, v48, v49 offset1:1
	v_add_u32_e32 v0, 0x30c0, v69
	ds_write2_b32 v0, v50, v51 offset1:1
	v_add_u32_e32 v0, 0x30c8, v69
	ds_write2_b32 v0, v52, v53 offset1:1
	v_add_u32_e32 v0, 0x34d0, v69
	ds_write2_b32 v0, v54, v55 offset1:1
	v_add_u32_e32 v0, 0x34d8, v69
	ds_write2_b32 v0, v56, v57 offset1:1
	v_add_u32_e32 v0, 0x38e0, v69
	ds_write2_b32 v0, v58, v59 offset1:1
	v_add_u32_e32 v0, 0x38e8, v69
	ds_write2_b32 v0, v60, v61 offset1:1
	v_add_u32_e32 v0, 0x3cf0, v69
	ds_write2_b32 v0, v62, v63 offset1:1
	v_add_u32_e32 v0, 0x3cf8, v69
	ds_write2_b32 v0, v64, v65 offset1:1
	s_waitcnt lgkmcnt(0)
	v_add_u32_e32 v26, 0x400, v87
	ds_read2_b32 v[8:9], v87 offset0:65 offset1:73
	ds_read2_b32 v[10:11], v87 offset1:8
	ds_read2_b32 v[12:13], v87 offset0:130 offset1:138
	ds_read2_b32 v[14:15], v87 offset0:195 offset1:203
	ds_read2_b32 v[16:17], v26 offset0:4 offset1:12
	ds_read2_b32 v[18:19], v26 offset0:69 offset1:77
	ds_read2_b32 v[20:21], v26 offset0:134 offset1:142
	ds_read2_b32 v[22:23], v26 offset0:199 offset1:207
	v_or_b32_e32 v0, s10, v86
	v_lshlrev_b64 v[24:25], 9, v[0:1]
	s_waitcnt lgkmcnt(6)
	v_cvt_pk_bf16_f32 v4, v10, v8
	s_waitcnt lgkmcnt(4)
	v_cvt_pk_bf16_f32 v5, v12, v14
	s_waitcnt lgkmcnt(2)
	v_cvt_pk_bf16_f32 v6, v16, v18
	s_waitcnt lgkmcnt(0)
	v_cvt_pk_bf16_f32 v7, v20, v22
	v_lshl_add_u64 v[24:25], v[2:3], 0, v[24:25]
	v_or_b32_e32 v0, s10, v88
	global_store_dwordx4 v[24:25], v[4:7], off nt
	s_nop 1
	v_cvt_pk_bf16_f32 v4, v11, v9
	v_lshlrev_b64 v[8:9], 9, v[0:1]
	v_cvt_pk_bf16_f32 v5, v13, v15
	v_cvt_pk_bf16_f32 v6, v17, v19
	v_cvt_pk_bf16_f32 v7, v21, v23
	v_lshl_add_u64 v[8:9], v[2:3], 0, v[8:9]
	global_store_dwordx4 v[8:9], v[4:7], off nt
	ds_read2_b32 v[8:9], v87 offset0:81 offset1:89
	ds_read2_b32 v[10:11], v87 offset0:16 offset1:24
	ds_read2_b32 v[12:13], v87 offset0:146 offset1:154
	ds_read2_b32 v[14:15], v87 offset0:211 offset1:219
	ds_read2_b32 v[16:17], v26 offset0:20 offset1:28
	ds_read2_b32 v[18:19], v26 offset0:85 offset1:93
	ds_read2_b32 v[20:21], v26 offset0:150 offset1:158
	ds_read2_b32 v[22:23], v26 offset0:215 offset1:223
	v_or_b32_e32 v0, s10, v89
	v_lshlrev_b64 v[24:25], 9, v[0:1]
	s_waitcnt lgkmcnt(6)
	v_cvt_pk_bf16_f32 v4, v10, v8
	s_waitcnt lgkmcnt(4)
	v_cvt_pk_bf16_f32 v5, v12, v14
	s_waitcnt lgkmcnt(2)
	v_cvt_pk_bf16_f32 v6, v16, v18
	s_waitcnt lgkmcnt(0)
	v_cvt_pk_bf16_f32 v7, v20, v22
	v_lshl_add_u64 v[24:25], v[2:3], 0, v[24:25]
	v_or_b32_e32 v0, s10, v90
	global_store_dwordx4 v[24:25], v[4:7], off nt
	s_nop 1
	v_cvt_pk_bf16_f32 v4, v11, v9
	v_lshlrev_b64 v[8:9], 9, v[0:1]
	v_cvt_pk_bf16_f32 v5, v13, v15
	v_cvt_pk_bf16_f32 v6, v17, v19
	v_cvt_pk_bf16_f32 v7, v21, v23
	v_lshl_add_u64 v[8:9], v[2:3], 0, v[8:9]
	global_store_dwordx4 v[8:9], v[4:7], off nt
	ds_read2_b32 v[8:9], v87 offset0:32 offset1:40
	ds_read2_b32 v[10:11], v87 offset0:97 offset1:105
	ds_read2_b32 v[12:13], v87 offset0:162 offset1:170
	ds_read2_b32 v[14:15], v87 offset0:227 offset1:235
	ds_read2_b32 v[16:17], v26 offset0:36 offset1:44
	ds_read2_b32 v[18:19], v26 offset0:101 offset1:109
	ds_read2_b32 v[20:21], v26 offset0:166 offset1:174
	ds_read2_b32 v[22:23], v26 offset0:231 offset1:239
	v_or_b32_e32 v0, s10, v91
	v_lshlrev_b64 v[24:25], 9, v[0:1]
	s_waitcnt lgkmcnt(6)
	v_cvt_pk_bf16_f32 v4, v8, v10
	s_waitcnt lgkmcnt(4)
	v_cvt_pk_bf16_f32 v5, v12, v14
	s_waitcnt lgkmcnt(2)
	v_cvt_pk_bf16_f32 v6, v16, v18
	s_waitcnt lgkmcnt(0)
	v_cvt_pk_bf16_f32 v7, v20, v22
	v_lshl_add_u64 v[24:25], v[2:3], 0, v[24:25]
	v_or_b32_e32 v0, s10, v92
	global_store_dwordx4 v[24:25], v[4:7], off nt
	s_nop 1
	v_cvt_pk_bf16_f32 v4, v9, v11
	v_lshlrev_b64 v[8:9], 9, v[0:1]
	v_cvt_pk_bf16_f32 v5, v13, v15
	v_cvt_pk_bf16_f32 v6, v17, v19
	v_cvt_pk_bf16_f32 v7, v21, v23
	v_lshl_add_u64 v[8:9], v[2:3], 0, v[8:9]
	global_store_dwordx4 v[8:9], v[4:7], off nt
	ds_read2_b32 v[8:9], v87 offset0:48 offset1:56
	ds_read2_b32 v[10:11], v87 offset0:113 offset1:121
	ds_read2_b32 v[12:13], v87 offset0:178 offset1:186
	ds_read2_b32 v[14:15], v87 offset0:243 offset1:251
	ds_read2_b32 v[16:17], v26 offset0:52 offset1:60
	ds_read2_b32 v[18:19], v26 offset0:117 offset1:125
	ds_read2_b32 v[20:21], v26 offset0:182 offset1:190
	ds_read2_b32 v[22:23], v26 offset0:247 offset1:255
	v_or_b32_e32 v0, s10, v93
	v_lshlrev_b64 v[24:25], 9, v[0:1]
	s_waitcnt lgkmcnt(6)
	v_cvt_pk_bf16_f32 v4, v8, v10
	s_waitcnt lgkmcnt(4)
	v_cvt_pk_bf16_f32 v5, v12, v14
	s_waitcnt lgkmcnt(2)
	v_cvt_pk_bf16_f32 v6, v16, v18
	s_waitcnt lgkmcnt(0)
	v_cvt_pk_bf16_f32 v7, v20, v22
	v_lshl_add_u64 v[24:25], v[2:3], 0, v[24:25]
	v_or_b32_e32 v0, s10, v94
	global_store_dwordx4 v[24:25], v[4:7], off nt
	s_nop 1
	v_cvt_pk_bf16_f32 v4, v9, v11
	v_lshlrev_b64 v[8:9], 9, v[0:1]
	v_cvt_pk_bf16_f32 v5, v13, v15
	v_cvt_pk_bf16_f32 v6, v17, v19
	v_cvt_pk_bf16_f32 v7, v21, v23
	v_lshl_add_u64 v[2:3], v[2:3], 0, v[8:9]
	global_store_dwordx4 v[2:3], v[4:7], off nt
	s_waitcnt lgkmcnt(0)

.LBB0_872:
	s_andn2_b64 vcc, exec, s[10:11]
	s_cbranch_vccnz .LBB0_874
	s_and_b32 s0, s17, 0xfc0
	s_add_i32 s10, s0, 0xfffff400
	s_and_b32 s12, s7, 0x3c0
	v_or_b32_e32 v0, s10, v66
	s_lshl_b32 s0, s12, 2
	v_or_b32_e32 v4, 4, v0
	v_mov_b32_e32 v5, v1
	v_lshl_add_u64 v[62:63], v[78:79], 0, s[0:1]
	v_lshlrev_b64 v[2:3], 12, v[0:1]
	v_lshlrev_b64 v[4:5], 12, v[4:5]
	v_lshl_add_u64 v[2:3], v[62:63], 0, v[2:3]
	v_lshl_add_u64 v[6:7], v[62:63], 0, v[4:5]
	global_load_dwordx4 v[2:5], v[2:3], off nt
	s_nop 0
	global_load_dwordx4 v[6:9], v[6:7], off nt
	v_or_b32_e32 v10, 8, v0
	v_mov_b32_e32 v11, v1
	v_or_b32_e32 v12, 12, v0
	v_mov_b32_e32 v13, v1
	v_lshlrev_b64 v[10:11], 12, v[10:11]
	v_lshlrev_b64 v[12:13], 12, v[12:13]
	v_lshl_add_u64 v[10:11], v[62:63], 0, v[10:11]
	v_lshl_add_u64 v[14:15], v[62:63], 0, v[12:13]
	global_load_dwordx4 v[10:13], v[10:11], off nt
	s_nop 0
	global_load_dwordx4 v[14:17], v[14:15], off nt
	v_or_b32_e32 v18, 16, v0
	v_mov_b32_e32 v19, v1
	v_or_b32_e32 v20, 20, v0
	v_mov_b32_e32 v21, v1
	v_lshlrev_b64 v[18:19], 12, v[18:19]
	v_lshlrev_b64 v[20:21], 12, v[20:21]
	v_lshl_add_u64 v[18:19], v[62:63], 0, v[18:19]
	v_lshl_add_u64 v[22:23], v[62:63], 0, v[20:21]
	global_load_dwordx4 v[18:21], v[18:19], off nt
	s_nop 0
	global_load_dwordx4 v[22:25], v[22:23], off nt
	v_or_b32_e32 v26, 24, v0
	v_mov_b32_e32 v27, v1
	v_or_b32_e32 v28, 28, v0
	v_mov_b32_e32 v29, v1
	v_lshlrev_b64 v[26:27], 12, v[26:27]
	v_lshlrev_b64 v[28:29], 12, v[28:29]
	v_lshl_add_u64 v[26:27], v[62:63], 0, v[26:27]
	v_lshl_add_u64 v[30:31], v[62:63], 0, v[28:29]
	global_load_dwordx4 v[26:29], v[26:27], off nt
	s_nop 0
	global_load_dwordx4 v[30:33], v[30:31], off nt
	v_or_b32_e32 v34, 32, v0
	v_mov_b32_e32 v35, v1
	v_or_b32_e32 v36, 36, v0
	v_mov_b32_e32 v37, v1
	v_lshlrev_b64 v[34:35], 12, v[34:35]
	v_lshlrev_b64 v[36:37], 12, v[36:37]
	v_lshl_add_u64 v[34:35], v[62:63], 0, v[34:35]
	v_lshl_add_u64 v[38:39], v[62:63], 0, v[36:37]
	global_load_dwordx4 v[34:37], v[34:35], off nt
	s_nop 0
	global_load_dwordx4 v[38:41], v[38:39], off nt
	v_or_b32_e32 v42, 40, v0
	v_mov_b32_e32 v43, v1
	v_or_b32_e32 v44, 44, v0
	v_mov_b32_e32 v45, v1
	v_lshlrev_b64 v[42:43], 12, v[42:43]
	v_lshlrev_b64 v[44:45], 12, v[44:45]
	v_lshl_add_u64 v[42:43], v[62:63], 0, v[42:43]
	v_lshl_add_u64 v[46:47], v[62:63], 0, v[44:45]
	global_load_dwordx4 v[42:45], v[42:43], off nt
	s_nop 0
	global_load_dwordx4 v[46:49], v[46:47], off nt
	v_or_b32_e32 v50, 48, v0
	v_mov_b32_e32 v51, v1
	v_lshlrev_b64 v[50:51], 12, v[50:51]
	v_lshl_add_u64 v[50:51], v[62:63], 0, v[50:51]
	v_or_b32_e32 v54, 52, v0
	v_mov_b32_e32 v55, v1
	global_load_dwordx4 v[50:53], v[50:51], off nt
	v_lshlrev_b64 v[54:55], 12, v[54:55]
	v_lshl_add_u64 v[54:55], v[62:63], 0, v[54:55]
	v_or_b32_e32 v58, 56, v0
	v_mov_b32_e32 v59, v1
	global_load_dwordx4 v[54:57], v[54:55], off nt
	v_lshlrev_b64 v[58:59], 12, v[58:59]
	v_lshl_add_u64 v[58:59], v[62:63], 0, v[58:59]
	v_or_b32_e32 v0, 60, v0
	global_load_dwordx4 v[58:61], v[58:59], off nt
	v_lshlrev_b64 v[64:65], 12, v[0:1]
	v_lshl_add_u64 v[62:63], v[62:63], 0, v[64:65]
	global_load_dwordx4 v[62:65], v[62:63], off nt
	v_add_u32_e32 v0, 0x410, v69
	s_mov_b32 s11, s1
	s_waitcnt vmcnt(0)
	ds_write2_b32 v69, v2, v3 offset1:1
	ds_write2_b32 v69, v4, v5 offset0:2 offset1:3
	ds_write2_b32 v0, v6, v7 offset1:1
	v_add_u32_e32 v0, 0x418, v69
	ds_write2_b32 v0, v8, v9 offset1:1
	v_add_u32_e32 v0, 0x820, v69
	ds_write2_b32 v0, v10, v11 offset1:1
	v_add_u32_e32 v0, 0x828, v69
	ds_write2_b32 v0, v12, v13 offset1:1
	v_add_u32_e32 v0, 0xc30, v69
	ds_write2_b32 v0, v14, v15 offset1:1
	v_add_u32_e32 v0, 0xc38, v69
	ds_write2_b32 v0, v16, v17 offset1:1
	v_add_u32_e32 v0, 0x1040, v69
	ds_write2_b32 v0, v18, v19 offset1:1
	v_add_u32_e32 v0, 0x1048, v69
	ds_write2_b32 v0, v20, v21 offset1:1
	v_add_u32_e32 v0, 0x1450, v69
	ds_write2_b32 v0, v22, v23 offset1:1
	v_add_u32_e32 v0, 0x1458, v69
	ds_write2_b32 v0, v24, v25 offset1:1
	v_add_u32_e32 v0, 0x1860, v69
	v_lshl_add_u64 v[22:23], s[10:11], 1, v[74:75]
	ds_write2_b32 v0, v26, v27 offset1:1
	v_add_u32_e32 v0, 0x1868, v69
	ds_write2_b32 v0, v28, v29 offset1:1
	v_add_u32_e32 v0, 0x1c70, v69
	ds_write2_b32 v0, v30, v31 offset1:1
	v_add_u32_e32 v0, 0x1c78, v69
	ds_write2_b32 v0, v32, v33 offset1:1
	v_add_u32_e32 v0, 0x2080, v69
	v_add_u32_e32 v26, 0x400, v87
	ds_write2_b32 v0, v34, v35 offset1:1
	v_add_u32_e32 v0, 0x2088, v69
	ds_write2_b32 v0, v36, v37 offset1:1
	v_add_u32_e32 v0, 0x2490, v69
	ds_write2_b32 v0, v38, v39 offset1:1
	v_add_u32_e32 v0, 0x2498, v69
	ds_write2_b32 v0, v40, v41 offset1:1
	v_add_u32_e32 v0, 0x28a0, v69
	ds_write2_b32 v0, v42, v43 offset1:1
	v_add_u32_e32 v0, 0x28a8, v69
	ds_write2_b32 v0, v44, v45 offset1:1
	v_add_u32_e32 v0, 0x2cb0, v69
	ds_write2_b32 v0, v46, v47 offset1:1
	v_add_u32_e32 v0, 0x2cb8, v69
	ds_write2_b32 v0, v48, v49 offset1:1
	v_add_u32_e32 v0, 0x30c0, v69
	ds_write2_b32 v0, v50, v51 offset1:1
	v_add_u32_e32 v0, 0x30c8, v69
	ds_write2_b32 v0, v52, v53 offset1:1
	v_add_u32_e32 v0, 0x34d0, v69
	ds_write2_b32 v0, v54, v55 offset1:1
	v_add_u32_e32 v0, 0x34d8, v69
	ds_write2_b32 v0, v56, v57 offset1:1
	v_add_u32_e32 v0, 0x38e0, v69
	ds_write2_b32 v0, v58, v59 offset1:1
	v_add_u32_e32 v0, 0x38e8, v69
	ds_write2_b32 v0, v60, v61 offset1:1
	v_add_u32_e32 v0, 0x3cf0, v69
	ds_write2_b32 v0, v62, v63 offset1:1
	v_add_u32_e32 v0, 0x3cf8, v69
	ds_write2_b32 v0, v64, v65 offset1:1
	s_waitcnt lgkmcnt(0)
	ds_read2_b32 v[6:7], v87 offset0:65 offset1:73
	ds_read2_b32 v[8:9], v87 offset1:8
	ds_read2_b32 v[10:11], v87 offset0:130 offset1:138
	ds_read2_b32 v[12:13], v87 offset0:195 offset1:203
	ds_read2_b32 v[14:15], v26 offset0:4 offset1:12
	ds_read2_b32 v[16:17], v26 offset0:69 offset1:77
	ds_read2_b32 v[18:19], v26 offset0:134 offset1:142
	ds_read2_b32 v[20:21], v26 offset0:199 offset1:207
	v_or_b32_e32 v0, s12, v86
	v_lshlrev_b32_e32 v0, 11, v0
	s_waitcnt lgkmcnt(6)
	v_cvt_pk_bf16_f32 v2, v8, v6
	s_waitcnt lgkmcnt(4)
	v_cvt_pk_bf16_f32 v3, v10, v12
	s_waitcnt lgkmcnt(2)
	v_cvt_pk_bf16_f32 v4, v14, v16
	s_waitcnt lgkmcnt(0)
	v_cvt_pk_bf16_f32 v5, v18, v20
	v_lshl_add_u64 v[24:25], v[22:23], 0, v[0:1]
	global_store_dwordx4 v[24:25], v[2:5], off nt
	v_or_b32_e32 v0, s12, v88
	v_lshlrev_b32_e32 v0, 11, v0
	v_cvt_pk_bf16_f32 v2, v9, v7
	v_cvt_pk_bf16_f32 v3, v11, v13
	v_cvt_pk_bf16_f32 v4, v15, v17
	v_cvt_pk_bf16_f32 v5, v19, v21
	ds_read2_b32 v[8:9], v87 offset0:81 offset1:89
	ds_read2_b32 v[10:11], v87 offset0:16 offset1:24
	ds_read2_b32 v[12:13], v87 offset0:146 offset1:154
	ds_read2_b32 v[14:15], v87 offset0:211 offset1:219
	ds_read2_b32 v[16:17], v26 offset0:20 offset1:28
	ds_read2_b32 v[18:19], v26 offset0:85 offset1:93
	ds_read2_b32 v[20:21], v26 offset0:150 offset1:158
	ds_read2_b32 v[24:25], v26 offset0:215 offset1:223
	v_lshl_add_u64 v[6:7], v[22:23], 0, v[0:1]
	v_or_b32_e32 v0, s12, v89
	v_lshlrev_b32_e32 v0, 11, v0
	global_store_dwordx4 v[6:7], v[2:5], off nt
	v_lshl_add_u64 v[6:7], v[22:23], 0, v[0:1]
	v_or_b32_e32 v0, s12, v90
	s_waitcnt lgkmcnt(6)
	v_cvt_pk_bf16_f32 v2, v10, v8
	s_waitcnt lgkmcnt(4)
	v_cvt_pk_bf16_f32 v3, v12, v14
	s_waitcnt lgkmcnt(2)
	v_cvt_pk_bf16_f32 v4, v16, v18
	s_waitcnt lgkmcnt(0)
	v_cvt_pk_bf16_f32 v5, v20, v24
	global_store_dwordx4 v[6:7], v[2:5], off nt
	v_lshlrev_b32_e32 v0, 11, v0
	v_lshl_add_u64 v[6:7], v[22:23], 0, v[0:1]
	v_cvt_pk_bf16_f32 v2, v11, v9
	v_cvt_pk_bf16_f32 v3, v13, v15
	v_cvt_pk_bf16_f32 v4, v17, v19
	v_cvt_pk_bf16_f32 v5, v21, v25
	ds_read2_b32 v[8:9], v87 offset0:32 offset1:40
	ds_read2_b32 v[10:11], v87 offset0:97 offset1:105
	ds_read2_b32 v[12:13], v87 offset0:162 offset1:170
	ds_read2_b32 v[14:15], v87 offset0:227 offset1:235
	ds_read2_b32 v[16:17], v26 offset0:36 offset1:44
	ds_read2_b32 v[18:19], v26 offset0:101 offset1:109
	ds_read2_b32 v[20:21], v26 offset0:166 offset1:174
	ds_read2_b32 v[24:25], v26 offset0:231 offset1:239
	v_or_b32_e32 v0, s12, v91
	v_lshlrev_b32_e32 v0, 11, v0
	global_store_dwordx4 v[6:7], v[2:5], off nt
	v_lshl_add_u64 v[6:7], v[22:23], 0, v[0:1]
	v_or_b32_e32 v0, s12, v92
	s_waitcnt lgkmcnt(6)
	v_cvt_pk_bf16_f32 v2, v8, v10
	s_waitcnt lgkmcnt(4)
	v_cvt_pk_bf16_f32 v3, v12, v14
	s_waitcnt lgkmcnt(2)
	v_cvt_pk_bf16_f32 v4, v16, v18
	s_waitcnt lgkmcnt(0)
	v_cvt_pk_bf16_f32 v5, v20, v24
	global_store_dwordx4 v[6:7], v[2:5], off nt
	v_lshlrev_b32_e32 v0, 11, v0
	v_lshl_add_u64 v[6:7], v[22:23], 0, v[0:1]
	v_cvt_pk_bf16_f32 v2, v9, v11
	v_cvt_pk_bf16_f32 v3, v13, v15
	v_cvt_pk_bf16_f32 v4, v17, v19
	v_cvt_pk_bf16_f32 v5, v21, v25
	ds_read2_b32 v[8:9], v87 offset0:48 offset1:56
	ds_read2_b32 v[10:11], v87 offset0:113 offset1:121
	ds_read2_b32 v[12:13], v87 offset0:178 offset1:186
	ds_read2_b32 v[14:15], v87 offset0:243 offset1:251
	ds_read2_b32 v[16:17], v26 offset0:52 offset1:60
	ds_read2_b32 v[18:19], v26 offset0:117 offset1:125
	ds_read2_b32 v[20:21], v26 offset0:182 offset1:190
	ds_read2_b32 v[24:25], v26 offset0:247 offset1:255
	v_or_b32_e32 v0, s12, v93
	v_lshlrev_b32_e32 v0, 11, v0
	global_store_dwordx4 v[6:7], v[2:5], off nt
	v_lshl_add_u64 v[6:7], v[22:23], 0, v[0:1]
	v_or_b32_e32 v0, s12, v94
	s_waitcnt lgkmcnt(6)
	v_cvt_pk_bf16_f32 v2, v8, v10
	s_waitcnt lgkmcnt(4)
	v_cvt_pk_bf16_f32 v3, v12, v14
	s_waitcnt lgkmcnt(2)
	v_cvt_pk_bf16_f32 v4, v16, v18
	s_waitcnt lgkmcnt(0)
	v_cvt_pk_bf16_f32 v5, v20, v24
	v_lshlrev_b32_e32 v0, 11, v0
	global_store_dwordx4 v[6:7], v[2:5], off nt
	v_lshl_add_u64 v[6:7], v[22:23], 0, v[0:1]
	s_nop 0
	v_cvt_pk_bf16_f32 v2, v9, v11
	v_cvt_pk_bf16_f32 v3, v13, v15
	v_cvt_pk_bf16_f32 v4, v17, v19
	v_cvt_pk_bf16_f32 v5, v21, v25
	global_store_dwordx4 v[6:7], v[2:5], off nt
	s_waitcnt lgkmcnt(0)

.LBB0_948:
	s_waitcnt vmcnt(0)
	v_pk_mul_f32 v[2:3], v[2:3], v[10:11] op_sel_hi:[1,0]
	v_add_u32_e32 v6, 0x2cb0, v89
	ds_write2_b32 v6, v2, v3 offset1:1
	v_pk_mul_f32 v[2:3], v[4:5], v[10:11] op_sel_hi:[1,0]
	v_add_u32_e32 v4, 0x2cb8, v89
	s_sext_i32_i16 s0, s0
	s_and_b32 s13, s16, 0x1fffffe
	ds_write2_b32 v4, v2, v3 offset1:1
	s_add_i32 s13, s13, s0
	s_waitcnt lgkmcnt(0)
	s_lshl_b32 s0, s13, 7
	s_and_b32 s12, s12, 64
	ds_read2_b32 v[8:9], v77 offset0:65 offset1:73
	ds_read2_b32 v[10:11], v77 offset1:8
	ds_read2_b32 v[12:13], v77 offset0:130 offset1:138
	ds_read2_b32 v[14:15], v77 offset0:195 offset1:203
	ds_read2_b32 v[16:17], v90 offset0:4 offset1:12
	ds_read2_b32 v[18:19], v90 offset0:69 offset1:77
	ds_read2_b32 v[20:21], v90 offset0:134 offset1:142
	ds_read2_b32 v[22:23], v90 offset0:199 offset1:207
	s_or_b32 s0, s0, s12
	v_or_b32_e32 v24, s0, v76
	v_ashrrev_i32_e32 v25, 31, v24
	v_lshl_add_u64 v[2:3], s[10:11], 1, v[70:71]
	v_lshlrev_b64 v[24:25], 11, v[24:25]
	s_waitcnt lgkmcnt(6)
	v_cvt_pk_bf16_f32 v4, v10, v8
	s_waitcnt lgkmcnt(4)
	v_cvt_pk_bf16_f32 v5, v12, v14
	s_waitcnt lgkmcnt(2)
	v_cvt_pk_bf16_f32 v6, v16, v18
	s_waitcnt lgkmcnt(0)
	v_cvt_pk_bf16_f32 v7, v20, v22
	v_lshl_add_u64 v[24:25], v[2:3], 0, v[24:25]
	v_or_b32_e32 v8, s0, v78
	global_store_dwordx4 v[24:25], v[4:7], off nt
	v_or_b32_e32 v24, s0, v79
	v_ashrrev_i32_e32 v25, 31, v24
	v_cvt_pk_bf16_f32 v4, v11, v9
	v_ashrrev_i32_e32 v9, 31, v8
	v_lshlrev_b64 v[8:9], 11, v[8:9]
	v_cvt_pk_bf16_f32 v5, v13, v15
	v_cvt_pk_bf16_f32 v6, v17, v19
	v_cvt_pk_bf16_f32 v7, v21, v23
	v_lshl_add_u64 v[8:9], v[2:3], 0, v[8:9]
	global_store_dwordx4 v[8:9], v[4:7], off nt
	ds_read2_b32 v[8:9], v77 offset0:81 offset1:89
	ds_read2_b32 v[10:11], v77 offset0:16 offset1:24
	ds_read2_b32 v[12:13], v77 offset0:146 offset1:154
	ds_read2_b32 v[14:15], v77 offset0:211 offset1:219
	ds_read2_b32 v[16:17], v90 offset0:20 offset1:28
	ds_read2_b32 v[18:19], v90 offset0:85 offset1:93
	ds_read2_b32 v[20:21], v90 offset0:150 offset1:158
	ds_read2_b32 v[22:23], v90 offset0:215 offset1:223
	v_lshlrev_b64 v[24:25], 11, v[24:25]
	s_waitcnt lgkmcnt(6)
	v_cvt_pk_bf16_f32 v4, v10, v8
	s_waitcnt lgkmcnt(4)
	v_cvt_pk_bf16_f32 v5, v12, v14
	s_waitcnt lgkmcnt(2)
	v_cvt_pk_bf16_f32 v6, v16, v18
	s_waitcnt lgkmcnt(0)
	v_cvt_pk_bf16_f32 v7, v20, v22
	v_lshl_add_u64 v[24:25], v[2:3], 0, v[24:25]
	v_or_b32_e32 v8, s0, v80
	global_store_dwordx4 v[24:25], v[4:7], off nt
	v_or_b32_e32 v24, s0, v81
	v_ashrrev_i32_e32 v25, 31, v24
	v_cvt_pk_bf16_f32 v4, v11, v9
	v_ashrrev_i32_e32 v9, 31, v8
	v_lshlrev_b64 v[8:9], 11, v[8:9]
	v_cvt_pk_bf16_f32 v5, v13, v15
	v_cvt_pk_bf16_f32 v6, v17, v19
	v_cvt_pk_bf16_f32 v7, v21, v23
	v_lshl_add_u64 v[8:9], v[2:3], 0, v[8:9]
	global_store_dwordx4 v[8:9], v[4:7], off nt
	ds_read2_b32 v[8:9], v77 offset0:32 offset1:40
	ds_read2_b32 v[10:11], v77 offset0:97 offset1:105
	ds_read2_b32 v[12:13], v77 offset0:162 offset1:170
	ds_read2_b32 v[14:15], v77 offset0:227 offset1:235
	ds_read2_b32 v[16:17], v90 offset0:36 offset1:44
	ds_read2_b32 v[18:19], v90 offset0:101 offset1:109
	ds_read2_b32 v[20:21], v90 offset0:166 offset1:174
	ds_read2_b32 v[22:23], v90 offset0:231 offset1:239
	v_lshlrev_b64 v[24:25], 11, v[24:25]
	s_waitcnt lgkmcnt(6)
	v_cvt_pk_bf16_f32 v4, v8, v10
	s_waitcnt lgkmcnt(4)
	v_cvt_pk_bf16_f32 v5, v12, v14
	s_waitcnt lgkmcnt(2)
	v_cvt_pk_bf16_f32 v6, v16, v18
	s_waitcnt lgkmcnt(0)
	v_cvt_pk_bf16_f32 v7, v20, v22
	v_lshl_add_u64 v[24:25], v[2:3], 0, v[24:25]
	v_or_b32_e32 v8, s0, v82
	global_store_dwordx4 v[24:25], v[4:7], off nt
	v_or_b32_e32 v24, s0, v83
	v_ashrrev_i32_e32 v25, 31, v24
	v_cvt_pk_bf16_f32 v4, v9, v11
	v_ashrrev_i32_e32 v9, 31, v8
	v_lshlrev_b64 v[8:9], 11, v[8:9]
	v_cvt_pk_bf16_f32 v5, v13, v15
	v_cvt_pk_bf16_f32 v6, v17, v19
	v_cvt_pk_bf16_f32 v7, v21, v23
	v_lshl_add_u64 v[8:9], v[2:3], 0, v[8:9]
	global_store_dwordx4 v[8:9], v[4:7], off nt
	ds_read2_b32 v[8:9], v77 offset0:48 offset1:56
	ds_read2_b32 v[10:11], v77 offset0:113 offset1:121
	ds_read2_b32 v[12:13], v77 offset0:178 offset1:186
	ds_read2_b32 v[14:15], v77 offset0:243 offset1:251
	ds_read2_b32 v[16:17], v90 offset0:52 offset1:60
	ds_read2_b32 v[18:19], v90 offset0:117 offset1:125
	ds_read2_b32 v[20:21], v90 offset0:182 offset1:190
	ds_read2_b32 v[22:23], v90 offset0:247 offset1:255
	v_lshlrev_b64 v[24:25], 11, v[24:25]
	s_waitcnt lgkmcnt(6)
	v_cvt_pk_bf16_f32 v4, v8, v10
	s_waitcnt lgkmcnt(4)
	v_cvt_pk_bf16_f32 v5, v12, v14
	s_waitcnt lgkmcnt(2)
	v_cvt_pk_bf16_f32 v6, v16, v18
	s_waitcnt lgkmcnt(0)
	v_cvt_pk_bf16_f32 v7, v20, v22
	v_lshl_add_u64 v[24:25], v[2:3], 0, v[24:25]
	v_or_b32_e32 v8, s0, v84
	global_store_dwordx4 v[24:25], v[4:7], off nt
	s_nop 1
	v_cvt_pk_bf16_f32 v4, v9, v11
	v_ashrrev_i32_e32 v9, 31, v8
	v_lshlrev_b64 v[8:9], 11, v[8:9]
	v_cvt_pk_bf16_f32 v5, v13, v15
	v_cvt_pk_bf16_f32 v6, v17, v19
	v_cvt_pk_bf16_f32 v7, v21, v23
	v_lshl_add_u64 v[2:3], v[2:3], 0, v[8:9]
	global_store_dwordx4 v[2:3], v[4:7], off nt
	s_waitcnt lgkmcnt(0)

.LBB0_950:
	s_mov_b64 s[10:11], -1
	s_cmpk_gt_i32 s8, 0x57f
	v_add_u32_e32 v90, 0x400, v77
	s_cbranch_scc0 .LBB0_952
	s_and_b32 s0, s6, 0x7fffffc0
	s_add_i32 s10, s0, 0xffffea00
	s_and_b32 s12, s9, 0x3c0
	v_or_b32_e32 v62, s10, v66
	s_lshl_b32 s0, s12, 2
	v_mov_b32_e32 v63, v1
	v_or_b32_e32 v4, 4, v62
	v_mov_b32_e32 v5, v1
	v_lshl_add_u64 v[64:65], v[72:73], 0, s[0:1]
	v_lshlrev_b64 v[2:3], 12, v[62:63]
	v_lshlrev_b64 v[4:5], 12, v[4:5]
	v_lshl_add_u64 v[2:3], v[64:65], 0, v[2:3]
	v_lshl_add_u64 v[6:7], v[64:65], 0, v[4:5]
	global_load_dwordx4 v[2:5], v[2:3], off nt
	s_nop 0
	global_load_dwordx4 v[6:9], v[6:7], off nt
	v_or_b32_e32 v10, 8, v62
	v_mov_b32_e32 v11, v1
	v_or_b32_e32 v12, 12, v62
	v_mov_b32_e32 v13, v1
	v_lshlrev_b64 v[10:11], 12, v[10:11]
	v_lshlrev_b64 v[12:13], 12, v[12:13]
	v_lshl_add_u64 v[10:11], v[64:65], 0, v[10:11]
	v_lshl_add_u64 v[14:15], v[64:65], 0, v[12:13]
	global_load_dwordx4 v[10:13], v[10:11], off nt
	s_nop 0
	global_load_dwordx4 v[14:17], v[14:15], off nt
	v_or_b32_e32 v18, 16, v62
	v_mov_b32_e32 v19, v1
	v_or_b32_e32 v20, 20, v62
	v_mov_b32_e32 v21, v1
	v_lshlrev_b64 v[18:19], 12, v[18:19]
	v_lshlrev_b64 v[20:21], 12, v[20:21]
	v_lshl_add_u64 v[18:19], v[64:65], 0, v[18:19]
	v_lshl_add_u64 v[22:23], v[64:65], 0, v[20:21]
	global_load_dwordx4 v[18:21], v[18:19], off nt
	s_nop 0
	global_load_dwordx4 v[22:25], v[22:23], off nt
	v_or_b32_e32 v26, 24, v62
	v_mov_b32_e32 v27, v1
	v_or_b32_e32 v28, 28, v62
	v_mov_b32_e32 v29, v1
	v_lshlrev_b64 v[26:27], 12, v[26:27]
	v_lshlrev_b64 v[28:29], 12, v[28:29]
	v_lshl_add_u64 v[26:27], v[64:65], 0, v[26:27]
	v_lshl_add_u64 v[30:31], v[64:65], 0, v[28:29]
	global_load_dwordx4 v[26:29], v[26:27], off nt
	s_nop 0
	global_load_dwordx4 v[30:33], v[30:31], off nt
	v_or_b32_e32 v34, 32, v62
	v_mov_b32_e32 v35, v1
	v_or_b32_e32 v36, 36, v62
	v_mov_b32_e32 v37, v1
	v_lshlrev_b64 v[34:35], 12, v[34:35]
	v_lshlrev_b64 v[36:37], 12, v[36:37]
	v_lshl_add_u64 v[34:35], v[64:65], 0, v[34:35]
	v_lshl_add_u64 v[38:39], v[64:65], 0, v[36:37]
	global_load_dwordx4 v[34:37], v[34:35], off nt
	s_nop 0
	global_load_dwordx4 v[38:41], v[38:39], off nt
	v_or_b32_e32 v42, 40, v62
	v_mov_b32_e32 v43, v1
	v_or_b32_e32 v44, 44, v62
	v_mov_b32_e32 v45, v1
	v_lshlrev_b64 v[42:43], 12, v[42:43]
	v_lshlrev_b64 v[44:45], 12, v[44:45]
	v_lshl_add_u64 v[42:43], v[64:65], 0, v[42:43]
	v_lshl_add_u64 v[46:47], v[64:65], 0, v[44:45]
	global_load_dwordx4 v[42:45], v[42:43], off nt
	s_nop 0
	global_load_dwordx4 v[46:49], v[46:47], off nt
	v_or_b32_e32 v50, 48, v62
	v_mov_b32_e32 v51, v1
	v_lshlrev_b64 v[50:51], 12, v[50:51]
	v_lshl_add_u64 v[50:51], v[64:65], 0, v[50:51]
	v_or_b32_e32 v54, 52, v62
	v_mov_b32_e32 v55, v1
	global_load_dwordx4 v[50:53], v[50:51], off nt
	v_lshlrev_b64 v[54:55], 12, v[54:55]
	v_lshl_add_u64 v[54:55], v[64:65], 0, v[54:55]
	v_or_b32_e32 v58, 56, v62
	v_mov_b32_e32 v59, v1
	global_load_dwordx4 v[54:57], v[54:55], off nt
	v_lshlrev_b64 v[58:59], 12, v[58:59]
	v_lshl_add_u64 v[58:59], v[64:65], 0, v[58:59]
	v_or_b32_e32 v62, 60, v62
	global_load_dwordx4 v[58:61], v[58:59], off nt
	v_lshlrev_b64 v[62:63], 12, v[62:63]
	v_lshl_add_u64 v[62:63], v[64:65], 0, v[62:63]
	global_load_dwordx4 v[62:65], v[62:63], off nt
	s_mov_b32 s11, s1
	s_waitcnt vmcnt(0)
	ds_write2_b32 v87, v2, v3 offset1:1
	ds_write2_b32 v87, v4, v5 offset0:2 offset1:3
	v_add_u32_e32 v2, 0x410, v87
	ds_write2_b32 v2, v6, v7 offset1:1
	v_add_u32_e32 v2, 0x418, v87
	ds_write2_b32 v2, v8, v9 offset1:1
	v_add_u32_e32 v2, 0x820, v87
	ds_write2_b32 v2, v10, v11 offset1:1
	v_add_u32_e32 v2, 0x828, v87
	ds_write2_b32 v2, v12, v13 offset1:1
	v_add_u32_e32 v2, 0xc30, v87
	ds_write2_b32 v2, v14, v15 offset1:1
	v_add_u32_e32 v2, 0xc38, v87
	ds_write2_b32 v2, v16, v17 offset1:1
	v_add_u32_e32 v2, 0x1040, v87
	ds_write2_b32 v2, v18, v19 offset1:1
	v_add_u32_e32 v2, 0x1048, v87
	ds_write2_b32 v2, v20, v21 offset1:1
	v_add_u32_e32 v2, 0x1450, v87
	ds_write2_b32 v2, v22, v23 offset1:1
	v_add_u32_e32 v2, 0x1458, v87
	ds_write2_b32 v2, v24, v25 offset1:1
	v_add_u32_e32 v2, 0x1860, v87
	v_lshl_add_u64 v[22:23], s[10:11], 1, v[68:69]
	ds_write2_b32 v2, v26, v27 offset1:1
	v_add_u32_e32 v2, 0x1868, v87
	ds_write2_b32 v2, v28, v29 offset1:1
	v_add_u32_e32 v2, 0x1c70, v87
	ds_write2_b32 v2, v30, v31 offset1:1
	v_add_u32_e32 v2, 0x1c78, v87
	ds_write2_b32 v2, v32, v33 offset1:1
	v_add_u32_e32 v2, 0x2080, v87
	v_mov_b32_e32 v25, v1
	ds_write2_b32 v2, v34, v35 offset1:1
	v_add_u32_e32 v2, 0x2088, v87
	ds_write2_b32 v2, v36, v37 offset1:1
	v_add_u32_e32 v2, 0x2490, v87
	ds_write2_b32 v2, v38, v39 offset1:1
	v_add_u32_e32 v2, 0x2498, v87
	ds_write2_b32 v2, v40, v41 offset1:1
	v_add_u32_e32 v2, 0x28a0, v87
	s_mov_b64 s[10:11], 0
	ds_write2_b32 v2, v42, v43 offset1:1
	v_add_u32_e32 v2, 0x28a8, v87
	ds_write2_b32 v2, v44, v45 offset1:1
	v_add_u32_e32 v2, 0x2cb0, v87
	ds_write2_b32 v2, v46, v47 offset1:1
	v_add_u32_e32 v2, 0x2cb8, v87
	ds_write2_b32 v2, v48, v49 offset1:1
	v_add_u32_e32 v2, 0x30c0, v87
	ds_write2_b32 v2, v50, v51 offset1:1
	v_add_u32_e32 v2, 0x30c8, v87
	ds_write2_b32 v2, v52, v53 offset1:1
	v_add_u32_e32 v2, 0x34d0, v87
	ds_write2_b32 v2, v54, v55 offset1:1
	v_add_u32_e32 v2, 0x34d8, v87
	ds_write2_b32 v2, v56, v57 offset1:1
	v_add_u32_e32 v2, 0x38e0, v87
	ds_write2_b32 v2, v58, v59 offset1:1
	v_add_u32_e32 v2, 0x38e8, v87
	ds_write2_b32 v2, v60, v61 offset1:1
	v_add_u32_e32 v2, 0x3cf0, v87
	ds_write2_b32 v2, v62, v63 offset1:1
	v_add_u32_e32 v2, 0x3cf8, v87
	ds_write2_b32 v2, v64, v65 offset1:1
	s_waitcnt lgkmcnt(0)
	ds_read2_b32 v[6:7], v77 offset0:65 offset1:73
	ds_read2_b32 v[8:9], v77 offset1:8
	ds_read2_b32 v[10:11], v77 offset0:130 offset1:138
	ds_read2_b32 v[12:13], v77 offset0:195 offset1:203
	ds_read2_b32 v[14:15], v90 offset0:4 offset1:12
	ds_read2_b32 v[16:17], v90 offset0:69 offset1:77
	ds_read2_b32 v[18:19], v90 offset0:134 offset1:142
	ds_read2_b32 v[20:21], v90 offset0:199 offset1:207
	s_waitcnt lgkmcnt(6)
	v_cvt_pk_bf16_f32 v2, v8, v6
	v_or_b32_e32 v6, s12, v76
	v_mul_u32_u24_e32 v6, 0xb00, v6
	v_lshlrev_b32_e32 v24, 1, v6
	s_waitcnt lgkmcnt(4)
	v_cvt_pk_bf16_f32 v3, v10, v12
	s_waitcnt lgkmcnt(2)
	v_cvt_pk_bf16_f32 v4, v14, v16
	s_waitcnt lgkmcnt(0)
	v_cvt_pk_bf16_f32 v5, v18, v20
	v_lshl_add_u64 v[24:25], v[22:23], 0, v[24:25]
	v_or_b32_e32 v6, s12, v78
	global_store_dwordx4 v[24:25], v[2:5], off nt
	v_mul_u32_u24_e32 v6, 0xb00, v6
	v_lshlrev_b32_e32 v6, 1, v6
	v_cvt_pk_bf16_f32 v2, v9, v7
	v_cvt_pk_bf16_f32 v3, v11, v13
	v_cvt_pk_bf16_f32 v4, v15, v17
	v_cvt_pk_bf16_f32 v5, v19, v21
	v_mov_b32_e32 v7, v1
	ds_read2_b32 v[8:9], v77 offset0:16 offset1:24
	ds_read2_b32 v[10:11], v77 offset0:81 offset1:89
	ds_read2_b32 v[12:13], v77 offset0:146 offset1:154
	ds_read2_b32 v[14:15], v77 offset0:211 offset1:219
	ds_read2_b32 v[16:17], v90 offset0:20 offset1:28
	ds_read2_b32 v[18:19], v90 offset0:85 offset1:93
	ds_read2_b32 v[20:21], v90 offset0:150 offset1:158
	ds_read2_b32 v[24:25], v90 offset0:215 offset1:223
	v_lshl_add_u64 v[6:7], v[22:23], 0, v[6:7]
	global_store_dwordx4 v[6:7], v[2:5], off nt
	v_or_b32_e32 v6, s12, v79
	v_mul_u32_u24_e32 v6, 0xb00, v6
	v_lshlrev_b32_e32 v6, 1, v6
	v_mov_b32_e32 v7, v1
	s_waitcnt lgkmcnt(6)
	v_cvt_pk_bf16_f32 v2, v8, v10
	s_waitcnt lgkmcnt(4)
	v_cvt_pk_bf16_f32 v3, v12, v14
	s_waitcnt lgkmcnt(2)
	v_cvt_pk_bf16_f32 v4, v16, v18
	s_waitcnt lgkmcnt(0)
	v_cvt_pk_bf16_f32 v5, v20, v24
	v_lshl_add_u64 v[6:7], v[22:23], 0, v[6:7]
	global_store_dwordx4 v[6:7], v[2:5], off nt
	v_or_b32_e32 v6, s12, v80
	v_mul_u32_u24_e32 v6, 0xb00, v6
	v_cvt_pk_bf16_f32 v2, v9, v11
	v_cvt_pk_bf16_f32 v3, v13, v15
	v_cvt_pk_bf16_f32 v4, v17, v19
	v_cvt_pk_bf16_f32 v5, v21, v25
	v_lshlrev_b32_e32 v6, 1, v6
	v_mov_b32_e32 v7, v1
	ds_read2_b32 v[8:9], v77 offset0:32 offset1:40
	ds_read2_b32 v[10:11], v77 offset0:97 offset1:105
	ds_read2_b32 v[12:13], v77 offset0:162 offset1:170
	ds_read2_b32 v[14:15], v77 offset0:227 offset1:235
	ds_read2_b32 v[16:17], v90 offset0:36 offset1:44
	ds_read2_b32 v[18:19], v90 offset0:101 offset1:109
	ds_read2_b32 v[20:21], v90 offset0:166 offset1:174
	ds_read2_b32 v[24:25], v90 offset0:231 offset1:239
	v_lshl_add_u64 v[6:7], v[22:23], 0, v[6:7]
	global_store_dwordx4 v[6:7], v[2:5], off nt
	v_or_b32_e32 v6, s12, v81
	v_mul_u32_u24_e32 v6, 0xb00, v6
	v_lshlrev_b32_e32 v6, 1, v6
	v_mov_b32_e32 v7, v1
	s_waitcnt lgkmcnt(6)
	v_cvt_pk_bf16_f32 v2, v8, v10
	s_waitcnt lgkmcnt(4)
	v_cvt_pk_bf16_f32 v3, v12, v14
	s_waitcnt lgkmcnt(2)
	v_cvt_pk_bf16_f32 v4, v16, v18
	s_waitcnt lgkmcnt(0)
	v_cvt_pk_bf16_f32 v5, v20, v24
	v_lshl_add_u64 v[6:7], v[22:23], 0, v[6:7]
	global_store_dwordx4 v[6:7], v[2:5], off nt
	v_or_b32_e32 v6, s12, v82
	v_mul_u32_u24_e32 v6, 0xb00, v6
	v_cvt_pk_bf16_f32 v2, v9, v11
	v_cvt_pk_bf16_f32 v3, v13, v15
	v_cvt_pk_bf16_f32 v4, v17, v19
	v_cvt_pk_bf16_f32 v5, v21, v25
	v_lshlrev_b32_e32 v6, 1, v6
	v_mov_b32_e32 v7, v1
	ds_read2_b32 v[8:9], v77 offset0:48 offset1:56
	ds_read2_b32 v[10:11], v77 offset0:113 offset1:121
	ds_read2_b32 v[12:13], v77 offset0:178 offset1:186
	ds_read2_b32 v[14:15], v77 offset0:243 offset1:251
	ds_read2_b32 v[16:17], v90 offset0:52 offset1:60
	ds_read2_b32 v[18:19], v90 offset0:117 offset1:125
	ds_read2_b32 v[20:21], v90 offset0:182 offset1:190
	ds_read2_b32 v[24:25], v90 offset0:247 offset1:255
	v_lshl_add_u64 v[6:7], v[22:23], 0, v[6:7]
	global_store_dwordx4 v[6:7], v[2:5], off nt
	v_or_b32_e32 v6, s12, v83
	v_mul_u32_u24_e32 v6, 0xb00, v6
	v_lshlrev_b32_e32 v6, 1, v6
	v_mov_b32_e32 v7, v1
	s_waitcnt lgkmcnt(6)
	v_cvt_pk_bf16_f32 v2, v8, v10
	s_waitcnt lgkmcnt(4)
	v_cvt_pk_bf16_f32 v3, v12, v14
	s_waitcnt lgkmcnt(2)
	v_cvt_pk_bf16_f32 v4, v16, v18
	s_waitcnt lgkmcnt(0)
	v_cvt_pk_bf16_f32 v5, v20, v24
	v_lshl_add_u64 v[6:7], v[22:23], 0, v[6:7]
	global_store_dwordx4 v[6:7], v[2:5], off nt
	v_or_b32_e32 v6, s12, v84
	v_mul_u32_u24_e32 v6, 0xb00, v6
	v_lshlrev_b32_e32 v6, 1, v6
	v_mov_b32_e32 v7, v1
	v_cvt_pk_bf16_f32 v2, v9, v11
	v_cvt_pk_bf16_f32 v3, v13, v15
	v_cvt_pk_bf16_f32 v4, v17, v19
	v_cvt_pk_bf16_f32 v5, v21, v25
	v_lshl_add_u64 v[6:7], v[22:23], 0, v[6:7]
	global_store_dwordx4 v[6:7], v[2:5], off nt
	s_waitcnt lgkmcnt(0)
